# C-attention loop: K/V LDS-DMA issue moved from the serial section between the QK and PV halves into late PV MFMA gaps (after MFMAs 21-23)
# speedup vs baseline: 1.0083x; 1.0083x over previous
.LBB0_442:
	s_mov_b32 s30, s62
	v_mov_b64_e32 v[218:219], v[96:97]
	s_mov_b32 s63, s33
	s_mov_b32 s3, s61
	v_lshl_add_u32 v206, s36, 14, v241
	ds_read_b64_tr_b16 v[196:197], v206 offset:24576
	ds_read_b64_tr_b16 v[198:199], v206 offset:25088
	v_add_f32_e32 v96, v80, v81
	v_add_f32_e32 v96, v82, v96
	v_add_f32_e32 v96, v83, v96
	v_add_f32_e32 v96, v84, v96
	v_add_f32_e32 v96, v85, v96
	v_cvt_pk_bf16_f32 v140, v80, v81
	v_cvt_pk_bf16_f32 v141, v82, v83
	v_mfma_f32_32x32x16_bf16 v[112:127], v[188:191], v[156:159], 0
	ds_read_b64_tr_b16 v[80:81], v206 offset:28672
	ds_read_b64_tr_b16 v[82:83], v206 offset:29184
	v_add_f32_e32 v96, v86, v96
	v_add_f32_e32 v96, v87, v96
	v_add_f32_e32 v96, v88, v96
	v_add_f32_e32 v128, v89, v96
	v_mfma_f32_32x32x16_bf16 v[96:111], v[180:183], v[156:159], 0
	v_cvt_pk_bf16_f32 v142, v84, v85
	v_cvt_pk_bf16_f32 v143, v86, v87
	ds_read_b64_tr_b16 v[84:85], v206 offset:25600
	ds_read_b64_tr_b16 v[86:87], v206 offset:26112
	v_add_f32_e32 v128, v90, v128
	v_add_f32_e32 v128, v91, v128
	v_add_f32_e32 v128, v92, v128
	v_add_f32_e32 v128, v93, v128
	v_cvt_pk_bf16_f32 v136, v88, v89
	v_cvt_pk_bf16_f32 v137, v90, v91
	v_mfma_f32_32x32x16_bf16 v[112:127], v[184:187], v[152:155], v[112:127]
	ds_read_b64_tr_b16 v[88:89], v206 offset:29696
	ds_read_b64_tr_b16 v[90:91], v206 offset:30208
	v_mfma_f32_32x32x16_bf16 v[96:111], v[176:179], v[152:155], v[96:111]
	v_add_f32_e32 v128, v94, v128
	v_add_f32_e32 v128, v95, v128
	v_add_f32_e32 v128, v64, v128
	v_add_f32_e32 v128, v65, v128
	v_cvt_pk_bf16_f32 v138, v92, v93
	v_cvt_pk_bf16_f32 v139, v94, v95
	ds_read_b64_tr_b16 v[92:93], v206 offset:26624
	ds_read_b64_tr_b16 v[94:95], v206 offset:27136
	v_add_f32_e32 v128, v66, v128
	v_add_f32_e32 v128, v67, v128
	v_add_f32_e32 v128, v68, v128
	v_add_f32_e32 v128, v69, v128
	v_cvt_pk_bf16_f32 v132, v64, v65
	v_cvt_pk_bf16_f32 v133, v66, v67
	v_mfma_f32_32x32x16_bf16 v[112:127], v[172:175], v[148:151], v[112:127]
	ds_read_b64_tr_b16 v[200:201], v206 offset:30720
	ds_read_b64_tr_b16 v[202:203], v206 offset:31232
	v_mfma_f32_32x32x16_bf16 v[96:111], v[168:171], v[148:151], v[96:111]
	v_add_f32_e32 v64, v70, v128
	v_add_f32_e32 v64, v71, v64
	v_add_f32_e32 v64, v72, v64
	v_add_f32_e32 v64, v73, v64
	v_cvt_pk_bf16_f32 v134, v68, v69
	v_cvt_pk_bf16_f32 v135, v70, v71
	ds_read_b64_tr_b16 v[242:243], v206 offset:27648
	ds_read_b64_tr_b16 v[244:245], v206 offset:28160
	v_add_f32_e32 v64, v74, v64
	v_add_f32_e32 v64, v75, v64
	v_add_f32_e32 v64, v76, v64
	v_add_f32_e32 v64, v77, v64
	v_cvt_pk_bf16_f32 v128, v72, v73
	v_cvt_pk_bf16_f32 v129, v74, v75
	v_mfma_f32_32x32x16_bf16 v[112:127], v[164:167], v[144:147], v[112:127]
	ds_read_b64_tr_b16 v[72:73], v206 offset:31744
	ds_read_b64_tr_b16 v[74:75], v206 offset:32256
	v_mfma_f32_32x32x16_bf16 v[96:111], v[160:163], v[144:147], v[96:111]
	v_add_f32_e32 v64, v78, v64
	v_add_f32_e32 v64, v79, v64
	v_add_f32_e32 v64, 0, v64
	v_cvt_pk_bf16_f32 v130, v76, v77
	v_cvt_pk_bf16_f32 v131, v78, v79
	v_add_f32_e32 v188, v204, v64
	s_waitcnt lgkmcnt(14)
	v_mfma_f32_32x32x16_bf16 v[48:63], v[140:143], v[196:199], v[48:63]
	v_exp_f32_e32 v112, v112
	v_exp_f32_e32 v113, v113
	ds_read_b64_tr_b16 v[76:77], v206 offset:32768
	ds_read_b64_tr_b16 v[78:79], v206 offset:33280
	s_waitcnt lgkmcnt(14)
	v_mfma_f32_32x32x16_bf16 v[32:47], v[140:143], v[80:83], v[32:47]
	v_exp_f32_e32 v114, v114
	v_exp_f32_e32 v115, v115
	ds_read_b64_tr_b16 v[80:81], v206 offset:36864
	ds_read_b64_tr_b16 v[82:83], v206 offset:37376
	s_waitcnt lgkmcnt(14)
	v_mfma_f32_32x32x16_bf16 v[48:63], v[136:139], v[84:87], v[48:63]
	v_exp_f32_e32 v116, v116
	v_exp_f32_e32 v117, v117
	ds_read_b64_tr_b16 v[84:85], v206 offset:33792
	ds_read_b64_tr_b16 v[86:87], v206 offset:34304
	s_waitcnt lgkmcnt(14)
	v_mfma_f32_32x32x16_bf16 v[32:47], v[136:139], v[88:91], v[32:47]
	v_exp_f32_e32 v118, v118
	v_exp_f32_e32 v119, v119
	ds_read_b64_tr_b16 v[88:89], v206 offset:37888
	ds_read_b64_tr_b16 v[90:91], v206 offset:38400
	s_waitcnt lgkmcnt(14)
	v_mfma_f32_32x32x16_bf16 v[48:63], v[132:135], v[92:95], v[48:63]
	v_exp_f32_e32 v120, v120
	v_exp_f32_e32 v121, v121
	ds_read_b64_tr_b16 v[92:93], v206 offset:34816
	ds_read_b64_tr_b16 v[94:95], v206 offset:35328
	s_waitcnt lgkmcnt(14)
	v_mfma_f32_32x32x16_bf16 v[32:47], v[132:135], v[200:203], v[32:47]
	v_exp_f32_e32 v122, v122
	v_exp_f32_e32 v123, v123
	ds_read_b64_tr_b16 v[196:197], v206 offset:38912
	ds_read_b64_tr_b16 v[198:199], v206 offset:39424
	s_waitcnt lgkmcnt(14)
	v_mfma_f32_32x32x16_bf16 v[48:63], v[128:131], v[242:245], v[48:63]
	v_exp_f32_e32 v124, v124
	v_exp_f32_e32 v125, v125
	ds_read_b64_tr_b16 v[200:201], v206 offset:35840
	ds_read_b64_tr_b16 v[202:203], v206 offset:36352
	s_waitcnt lgkmcnt(14)
	v_mfma_f32_32x32x16_bf16 v[32:47], v[128:131], v[72:75], v[32:47]
	v_exp_f32_e32 v126, v126
	v_exp_f32_e32 v127, v127
	ds_read_b64_tr_b16 v[72:73], v206 offset:39936
	ds_read_b64_tr_b16 v[74:75], v206 offset:40448
	s_waitcnt lgkmcnt(14)
	v_mfma_f32_32x32x16_bf16 v[16:31], v[140:143], v[76:79], v[16:31]
	v_exp_f32_e32 v96, v96
	v_exp_f32_e32 v97, v97
	s_lshl_b32 s31, s62, 13
	v_add_u32_e32 v160, s31, v239
	ds_read_b128 v[68:71], v160
	ds_read_b128 v[64:67], v160 offset:512
	s_waitcnt lgkmcnt(14)
	v_mfma_f32_32x32x16_bf16 v[0:15], v[140:143], v[80:83], v[0:15]
	v_exp_f32_e32 v98, v98
	v_exp_f32_e32 v99, v99
	ds_read_b128 v[180:183], v160 offset:2048
	ds_read_b128 v[176:179], v160 offset:2560
	s_waitcnt lgkmcnt(14)
	v_mfma_f32_32x32x16_bf16 v[16:31], v[136:139], v[84:87], v[16:31]
	v_exp_f32_e32 v100, v100
	v_exp_f32_e32 v101, v101
	ds_read_b128 v[172:175], v160 offset:4096
	ds_read_b128 v[168:171], v160 offset:4608
	s_waitcnt lgkmcnt(14)
	v_mfma_f32_32x32x16_bf16 v[0:15], v[136:139], v[88:91], v[0:15]
	v_exp_f32_e32 v102, v102
	v_exp_f32_e32 v103, v103
	ds_read_b128 v[164:167], v160 offset:6144
	ds_read_b128 v[160:163], v160 offset:6656
	s_waitcnt lgkmcnt(14)
	v_mfma_f32_32x32x16_bf16 v[16:31], v[132:135], v[92:95], v[16:31]
	v_exp_f32_e32 v104, v104
	v_exp_f32_e32 v105, v105
	v_lshl_add_u64 v[246:247], v[194:195], 0, s[4:5]
	s_mov_b64 s[34:35], 0xb622a00
	s_lshl_b32 s31, s61, 13
	v_lshl_add_u64 v[250:251], v[246:247], 0, s[34:35]
	s_add_i32 s31, s31, s58
	s_mov_b32 m0, s31
	s_nop 0
	global_load_lds_dwordx4 v[250:251], off
	s_waitcnt lgkmcnt(12)
	v_mfma_f32_32x32x16_bf16 v[0:15], v[132:135], v[196:199], v[0:15]
	v_exp_f32_e32 v106, v106
	v_exp_f32_e32 v107, v107
	v_lshl_add_u64 v[248:249], v[192:193], 0, s[4:5]
	s_mov_b64 s[34:35], 0xb412e00
	s_lshl_b32 s64, s62, 14
	v_lshl_add_u64 v[250:251], v[248:249], 0, s[34:35]
	s_add_i32 s31, s64, s59
	s_mov_b32 m0, s31
	s_nop 0
	global_load_lds_dwordx4 v[250:251], off
	s_waitcnt lgkmcnt(10)
	v_mfma_f32_32x32x16_bf16 v[16:31], v[128:131], v[200:203], v[16:31]
	v_exp_f32_e32 v108, v108
	v_exp_f32_e32 v109, v109
	s_mov_b64 s[34:35], 0xb412e80
	v_lshl_add_u64 v[250:251], v[248:249], 0, s[34:35]
	s_addk_i32 s31, 0x2000
	s_mov_b32 m0, s31
	s_nop 0
	global_load_lds_dwordx4 v[250:251], off
	s_waitcnt lgkmcnt(8)
	v_mfma_f32_32x32x16_bf16 v[0:15], v[128:131], v[72:75], v[0:15]
	v_exp_f32_e32 v110, v110
	v_exp_f32_e32 v111, v111
	s_waitcnt vmcnt(3) lgkmcnt(0)
	s_barrier
	s_add_i32 s33, s62, 1
	s_cmp_lg_u32 s62, 2
	s_cselect_b32 s61, s33, 0
	v_lshl_add_u32 v200, s3, 14, v241
	ds_read_b64_tr_b16 v[196:197], v200 offset:24576
	ds_read_b64_tr_b16 v[198:199], v200 offset:25088
	v_mfma_f32_32x32x16_bf16 v[80:95], v[68:71], v[156:159], 0
	v_add_f32_e32 v72, v112, v113
	v_add_f32_e32 v72, v114, v72
	v_add_f32_e32 v72, v115, v72
	v_add_f32_e32 v72, v116, v72
	v_add_f32_e32 v72, v117, v72
	v_cvt_pk_bf16_f32 v140, v112, v113
	v_cvt_pk_bf16_f32 v141, v114, v115
	ds_read_b64_tr_b16 v[112:113], v200 offset:28672
	ds_read_b64_tr_b16 v[114:115], v200 offset:29184
	v_add_f32_e32 v68, v118, v72
	v_add_f32_e32 v68, v119, v68
	v_add_f32_e32 v68, v120, v68
	v_add_f32_e32 v128, v121, v68
	v_mfma_f32_32x32x16_bf16 v[64:79], v[64:67], v[156:159], 0
	v_cvt_pk_bf16_f32 v142, v116, v117
	v_cvt_pk_bf16_f32 v143, v118, v119
	ds_read_b64_tr_b16 v[116:117], v200 offset:25600
	ds_read_b64_tr_b16 v[118:119], v200 offset:26112
	v_mfma_f32_32x32x16_bf16 v[80:95], v[180:183], v[152:155], v[80:95]
	v_add_f32_e32 v128, v122, v128
	v_add_f32_e32 v128, v123, v128
	v_add_f32_e32 v128, v124, v128
	v_add_f32_e32 v128, v125, v128
	v_cvt_pk_bf16_f32 v136, v120, v121
	v_cvt_pk_bf16_f32 v137, v122, v123
	ds_read_b64_tr_b16 v[120:121], v200 offset:29696
	ds_read_b64_tr_b16 v[122:123], v200 offset:30208
	v_mfma_f32_32x32x16_bf16 v[64:79], v[176:179], v[152:155], v[64:79]
	v_add_f32_e32 v128, v126, v128
	v_add_f32_e32 v128, v127, v128
	v_add_f32_e32 v128, v96, v128
	v_add_f32_e32 v128, v97, v128
	v_cvt_pk_bf16_f32 v138, v124, v125
	v_cvt_pk_bf16_f32 v139, v126, v127
	ds_read_b64_tr_b16 v[124:125], v200 offset:26624
	ds_read_b64_tr_b16 v[126:127], v200 offset:27136
	v_mfma_f32_32x32x16_bf16 v[80:95], v[172:175], v[148:151], v[80:95]
	v_add_f32_e32 v128, v98, v128
	v_add_f32_e32 v128, v99, v128
	v_add_f32_e32 v128, v100, v128
	v_add_f32_e32 v128, v101, v128
	v_cvt_pk_bf16_f32 v132, v96, v97
	v_cvt_pk_bf16_f32 v133, v98, v99
	ds_read_b64_tr_b16 v[96:97], v200 offset:30720
	ds_read_b64_tr_b16 v[98:99], v200 offset:31232
	v_mfma_f32_32x32x16_bf16 v[64:79], v[168:171], v[148:151], v[64:79]
	v_add_f32_e32 v128, v102, v128
	v_add_f32_e32 v128, v103, v128
	v_add_f32_e32 v128, v104, v128
	v_add_f32_e32 v128, v105, v128
	v_cvt_pk_bf16_f32 v134, v100, v101
	v_cvt_pk_bf16_f32 v135, v102, v103
	ds_read_b64_tr_b16 v[100:101], v200 offset:27648
	ds_read_b64_tr_b16 v[102:103], v200 offset:28160
	v_mfma_f32_32x32x16_bf16 v[80:95], v[164:167], v[144:147], v[80:95]
	v_add_f32_e32 v128, v106, v128
	v_add_f32_e32 v128, v107, v128
	v_add_f32_e32 v128, v108, v128
	v_add_f32_e32 v164, v109, v128
	v_cvt_pk_bf16_f32 v128, v104, v105
	v_cvt_pk_bf16_f32 v129, v106, v107
	ds_read_b64_tr_b16 v[104:105], v200 offset:31744
	ds_read_b64_tr_b16 v[106:107], v200 offset:32256
	v_mfma_f32_32x32x16_bf16 v[64:79], v[160:163], v[144:147], v[64:79]
	v_add_f32_e32 v130, v110, v164
	v_add_f32_e32 v130, v111, v130
	v_add_f32_e32 v160, 0, v130
	v_cvt_pk_bf16_f32 v130, v108, v109
	v_cvt_pk_bf16_f32 v131, v110, v111
	v_add_f32_e32 v204, v188, v160
	s_add_i32 s60, s60, 2
	s_waitcnt lgkmcnt(14)
	v_mfma_f32_32x32x16_bf16 v[48:63], v[140:143], v[196:199], v[48:63]
	v_exp_f32_e32 v80, v80
	v_exp_f32_e32 v81, v81
	ds_read_b64_tr_b16 v[108:109], v200 offset:32768
	ds_read_b64_tr_b16 v[110:111], v200 offset:33280
	s_waitcnt lgkmcnt(14)
	v_mfma_f32_32x32x16_bf16 v[32:47], v[140:143], v[112:115], v[32:47]
	v_exp_f32_e32 v82, v82
	v_exp_f32_e32 v83, v83
	ds_read_b64_tr_b16 v[112:113], v200 offset:36864
	ds_read_b64_tr_b16 v[114:115], v200 offset:37376
	s_waitcnt lgkmcnt(14)
	v_mfma_f32_32x32x16_bf16 v[48:63], v[136:139], v[116:119], v[48:63]
	v_exp_f32_e32 v84, v84
	v_exp_f32_e32 v85, v85
	ds_read_b64_tr_b16 v[116:117], v200 offset:33792
	ds_read_b64_tr_b16 v[118:119], v200 offset:34304
	s_waitcnt lgkmcnt(14)
	v_mfma_f32_32x32x16_bf16 v[32:47], v[136:139], v[120:123], v[32:47]
	v_exp_f32_e32 v86, v86
	v_exp_f32_e32 v87, v87
	ds_read_b64_tr_b16 v[120:121], v200 offset:37888
	ds_read_b64_tr_b16 v[122:123], v200 offset:38400
	s_waitcnt lgkmcnt(14)
	v_mfma_f32_32x32x16_bf16 v[48:63], v[132:135], v[124:127], v[48:63]
	v_exp_f32_e32 v88, v88
	v_exp_f32_e32 v89, v89
	ds_read_b64_tr_b16 v[124:125], v200 offset:34816
	ds_read_b64_tr_b16 v[126:127], v200 offset:35328
	s_waitcnt lgkmcnt(14)
	v_mfma_f32_32x32x16_bf16 v[32:47], v[132:135], v[96:99], v[32:47]
	v_exp_f32_e32 v90, v90
	v_exp_f32_e32 v91, v91
	ds_read_b64_tr_b16 v[96:97], v200 offset:38912
	ds_read_b64_tr_b16 v[98:99], v200 offset:39424
	s_waitcnt lgkmcnt(14)
	v_mfma_f32_32x32x16_bf16 v[48:63], v[128:131], v[100:103], v[48:63]
	v_exp_f32_e32 v92, v92
	v_exp_f32_e32 v93, v93
	ds_read_b64_tr_b16 v[100:101], v200 offset:35840
	ds_read_b64_tr_b16 v[102:103], v200 offset:36352
	s_waitcnt lgkmcnt(14)
	v_mfma_f32_32x32x16_bf16 v[32:47], v[128:131], v[104:107], v[32:47]
	v_exp_f32_e32 v94, v94
	v_exp_f32_e32 v95, v95
	ds_read_b64_tr_b16 v[104:105], v200 offset:39936
	ds_read_b64_tr_b16 v[106:107], v200 offset:40448
	s_waitcnt lgkmcnt(14)
	v_mfma_f32_32x32x16_bf16 v[16:31], v[140:143], v[108:111], v[16:31]
	v_exp_f32_e32 v64, v64
	v_exp_f32_e32 v65, v65
	v_lshl_add_u32 v160, s61, 13, v239
	ds_read_b128 v[188:191], v160
	ds_read_b128 v[180:183], v160 offset:512
	s_waitcnt lgkmcnt(14)
	v_mfma_f32_32x32x16_bf16 v[0:15], v[140:143], v[112:115], v[0:15]
	v_exp_f32_e32 v66, v66
	v_exp_f32_e32 v67, v67
	ds_read_b128 v[184:187], v160 offset:2048
	ds_read_b128 v[176:179], v160 offset:2560
	s_waitcnt lgkmcnt(14)
	v_mfma_f32_32x32x16_bf16 v[16:31], v[136:139], v[116:119], v[16:31]
	v_exp_f32_e32 v68, v68
	v_exp_f32_e32 v69, v69
	ds_read_b128 v[172:175], v160 offset:4096
	ds_read_b128 v[168:171], v160 offset:4608
	s_waitcnt lgkmcnt(14)
	v_mfma_f32_32x32x16_bf16 v[0:15], v[136:139], v[120:123], v[0:15]
	v_exp_f32_e32 v70, v70
	v_exp_f32_e32 v71, v71
	ds_read_b128 v[164:167], v160 offset:6144
	ds_read_b128 v[160:163], v160 offset:6656
	s_waitcnt lgkmcnt(14)
	v_mfma_f32_32x32x16_bf16 v[16:31], v[132:135], v[124:127], v[16:31]
	v_exp_f32_e32 v72, v72
	v_exp_f32_e32 v73, v73
	s_mov_b64 s[34:35], 0xb72aa00
	v_lshl_add_u64 v[250:251], v[246:247], 0, s[34:35]
	s_lshl_b32 s3, s62, 13
	s_add_i32 s3, s3, s58
	s_mov_b32 m0, s3
	s_nop 0
	global_load_lds_dwordx4 v[250:251], off
	s_waitcnt lgkmcnt(12)
	v_mfma_f32_32x32x16_bf16 v[0:15], v[132:135], v[96:99], v[0:15]
	v_exp_f32_e32 v74, v74
	v_exp_f32_e32 v75, v75
	s_mov_b64 s[34:35], 0xb51ae00
	s_lshl_b32 s31, s61, 14
	v_lshl_add_u64 v[250:251], v[248:249], 0, s[34:35]
	s_add_i32 s3, s31, s59
	s_mov_b32 m0, s3
	s_nop 0
	global_load_lds_dwordx4 v[250:251], off
	s_waitcnt lgkmcnt(10)
	v_mfma_f32_32x32x16_bf16 v[16:31], v[128:131], v[100:103], v[16:31]
	v_exp_f32_e32 v76, v76
	v_exp_f32_e32 v77, v77
	s_mov_b64 s[34:35], 0xb51ae80
	v_lshl_add_u64 v[250:251], v[248:249], 0, s[34:35]
	s_addk_i32 s3, 0x2000
	s_mov_b32 m0, s3
	s_nop 0
	global_load_lds_dwordx4 v[250:251], off
	s_waitcnt lgkmcnt(8)
	v_mfma_f32_32x32x16_bf16 v[0:15], v[128:131], v[104:107], v[0:15]
	v_exp_f32_e32 v78, v78
	v_exp_f32_e32 v79, v79
	s_add_i32 s3, s61, 1
	s_waitcnt vmcnt(3) lgkmcnt(0)
	s_barrier
	s_cmp_lg_u32 s61, 2
	s_cselect_b32 s62, s3, 0
	s_add_i32 s33, s63, 2
	v_lshl_add_u64 v[192:193], v[192:193], 0, s[12:13]
	v_lshl_add_u64 v[194:195], v[194:195], 0, s[12:13]
	s_cmp_ge_u32 s60, s42
	v_lshl_add_u64 v[96:97], v[218:219], 0, s[12:13]
	s_mov_b32 s36, s30
	s_cbranch_scc0 .LBB0_442
	s_add_i32 s3, s60, 1
	s_cmp_ge_u32 s3, s41
	v_readlane_b32 s65, v252, 9
	s_cbranch_scc1 .LBB0_477
